# attention: end-of-chunk lgkmcnt(0) for the bias reads moved to their first consumer (next chunk's first MFMAs, covered by the in-order K fragment read waits) so the barrier does not wait for them
# baseline (speedup 1.0000x reference)
; __device__ __forceinline__ void attn_phase(const Params& P, char* smem_raw) {
;     ...
;       __syncthreads();
;       f32x4 sacc[8];
; #pragma unroll
;       for (int t8 = 0; t8 < 8; ++t8) sacc[t8] = f32x4{0.f, 0.f, 0.f, 0.f};
; #pragma unroll
;       for (int s = 0; s < 2; ++s)
; #pragma unroll
;         for (int t8 = 0; t8 < 8; ++t8) {
;           const bf16x8 kf = *reinterpret_cast<const bf16x8*>(&sm_k[(t8 * 16 + (lane_c & 15)) * LDSS + s * 32 + (lane_c >> 4) * 8]);
;           sacc[t8] = __builtin_amdgcn_mfma_f32_16x16x32_bf16(qf[s], kf, sacc[t8], 0, 0, 0);
;         }
;       if (ck < 5) {
;         ATT_ISSUE(t, ck + 1)
;       } else if (t + VGRID < 8192) {
;         ATT_ISSUE(t + VGRID, 0)
;         ATT_QLOAD(t + VGRID)
;       }
;       if (ck < 4) {
;         const float* rb0 = sm_rpb + (rs + ck * 2 - r + 7) * 31;
; #pragma unroll
;         for (int t8 = 0; t8 < 8; ++t8)
; #pragma unroll
;           for (int reg = 0; reg < 4; ++reg)
;             sacc[t8][reg] += rb0[(t8 >> 2) * 31 + dco[reg][t8 & 3]];
;       }
; #pragma unroll
;       for (int reg = 0; reg < 4; ++reg) {
;         float mx = sacc[0][reg];
; #pragma unroll
;         for (int t8 = 1; t8 < 8; ++t8) mx = fmaxf(mx, sacc[t8][reg]);
;         mx = row16_max(mx);
;         const float mnew = fmaxf(mrow[reg], mx);
;         const float alpha = __builtin_amdgcn_exp2f(mrow[reg] - mnew);
;         mrow[reg] = mnew;
;         float rsum = 0.f;
; #pragma unroll
;         for (int t8 = 0; t8 < 8; ++t8) {
;           const float p = __builtin_amdgcn_exp2f(sacc[t8][reg] - mnew);
;           rsum += p;
;           sm_p[(wid * 16 + (lane_c >> 4) * 4 + reg) * 136 + t8 * 16 + (lane_c & 15)] = f2bf(p);
;         }
;         rsum = row16_sum(rsum);
;         lrow[reg] = lrow[reg] * alpha + rsum;
; #pragma unroll
;         for (int td = 0; td < 4; ++td) o[td][reg] *= alpha;
;       }
;       asm volatile("s_waitcnt lgkmcnt(0)" ::: "memory");
; #pragma unroll
;       for (int s4 = 0; s4 < 4; ++s4) {
;         const bf16x8 pf = *reinterpret_cast<const bf16x8*>(&sm_p[(wid * 16 + (lane_c & 15)) * 136 + s4 * 32 + (lane_c >> 4) * 8]);
; #pragma unroll
;         for (int td = 0; td < 4; ++td) {
;           const bf16x8 vf = *reinterpret_cast<const bf16x8*>(&sm_vt[(td * 16 + (lane_c & 15)) * 136 + s4 * 32 + (lane_c >> 4) * 8]);
;           o[td] = __builtin_amdgcn_mfma_f32_16x16x32_bf16(pf, vf, o[td], 0, 0, 0);
.Lmy_att_tile:
	s_barrier
	ds_read_b128 v[112:115], v144 offset:0
	ds_read_b128 v[116:119], v145 offset:0
	ds_read_b128 v[120:123], v144 offset:8192
	ds_read_b128 v[124:127], v145 offset:8192
	ds_read_b128 v[128:131], v144 offset:2048
	ds_read_b128 v[132:135], v145 offset:2048
	ds_read_b128 v[136:139], v144 offset:10240
	ds_read_b128 v[140:143], v145 offset:10240
	s_waitcnt lgkmcnt(7)
	v_mfma_f32_16x16x32_bf16 v[0:3], v[112:115], v[64:67], v[0:3]
	s_waitcnt lgkmcnt(6)
	v_mfma_f32_16x16x32_bf16 v[0:3], v[116:119], v[68:71], v[0:3]
	s_waitcnt lgkmcnt(5)
	v_mfma_f32_16x16x32_bf16 v[4:7], v[120:123], v[64:67], v[4:7]
	s_waitcnt lgkmcnt(4)
	v_mfma_f32_16x16x32_bf16 v[4:7], v[124:127], v[68:71], v[4:7]
	s_waitcnt lgkmcnt(3)
	v_mfma_f32_16x16x32_bf16 v[8:11], v[128:131], v[64:67], v[8:11]
	s_waitcnt lgkmcnt(2)
	v_mfma_f32_16x16x32_bf16 v[8:11], v[132:135], v[68:71], v[8:11]
	s_waitcnt lgkmcnt(1)
	v_mfma_f32_16x16x32_bf16 v[12:15], v[136:139], v[64:67], v[12:15]
	s_waitcnt lgkmcnt(0)
	v_mfma_f32_16x16x32_bf16 v[12:15], v[140:143], v[68:71], v[12:15]
	s_nop 7
	v_max3_f32 v203, v0, v1, v2
	v_max3_f32 v203, v203, v3, v4
	v_max3_f32 v203, v203, v5, v6
	v_max3_f32 v203, v203, v7, v8
	v_max3_f32 v203, v203, v9, v10
	v_max3_f32 v203, v203, v11, v12
	v_max3_f32 v203, v203, v13, v14
	v_max_f32_e32 v203, v203, v15
	v_mov_b32_e32 v205, v203
	s_nop 1
	v_permlane16_swap_b32_e32 v203, v205
	v_max_f32_e32 v203, v203, v205
	v_mov_b32_e32 v205, v203
	s_nop 1
	v_permlane32_swap_b32_e32 v203, v205
	v_max_f32_e32 v203, v203, v205
	v_max_f32_e32 v218, v200, v203
	v_sub_f32_e32 v220, v200, v218
	v_mov_b32_e32 v219, v218
	v_exp_f32_e32 v220, v220
	v_mov_b32_e32 v200, v218
	v_pk_add_f32 v[0:1], v[0:1], v[218:219] neg_lo:[0,1] neg_hi:[0,1]
	v_pk_add_f32 v[2:3], v[2:3], v[218:219] neg_lo:[0,1] neg_hi:[0,1]
	v_pk_add_f32 v[4:5], v[4:5], v[218:219] neg_lo:[0,1] neg_hi:[0,1]
	v_pk_add_f32 v[6:7], v[6:7], v[218:219] neg_lo:[0,1] neg_hi:[0,1]
	v_pk_add_f32 v[8:9], v[8:9], v[218:219] neg_lo:[0,1] neg_hi:[0,1]
	v_pk_add_f32 v[10:11], v[10:11], v[218:219] neg_lo:[0,1] neg_hi:[0,1]
	v_pk_add_f32 v[12:13], v[12:13], v[218:219] neg_lo:[0,1] neg_hi:[0,1]
	v_pk_add_f32 v[14:15], v[14:15], v[218:219] neg_lo:[0,1] neg_hi:[0,1]
	v_exp_f32_e32 v0, v0
	s_waitcnt vmcnt(4)
	v_exp_f32_e32 v1, v1
	ds_write_b128 v150, v[80:83] offset:32768
	v_exp_f32_e32 v2, v2
	ds_write_b128 v150, v[84:87] offset:36864
	v_exp_f32_e32 v3, v3
	ds_write_b128 v150, v[88:91] offset:40960
	v_exp_f32_e32 v4, v4
	ds_write_b128 v150, v[92:95] offset:45056
	v_exp_f32_e32 v5, v5
	ds_write_b64 v151, v[96:97] offset:32768
	v_exp_f32_e32 v6, v6
	ds_write_b64 v229, v[98:99] offset:32768
	v_exp_f32_e32 v7, v7
	ds_write_b64 v151, v[100:101] offset:36864
	v_exp_f32_e32 v8, v8
	ds_write_b64 v229, v[102:103] offset:36864
	v_exp_f32_e32 v9, v9
	ds_write_b64 v151, v[104:105] offset:40960
	v_exp_f32_e32 v10, v10
	ds_write_b64 v229, v[106:107] offset:40960
	v_exp_f32_e32 v11, v11
	ds_write_b64 v151, v[108:109] offset:45056
	v_exp_f32_e32 v12, v12
	ds_write_b64 v229, v[110:111] offset:45056
	v_exp_f32_e32 v13, v13
	s_add_u32 s100, s12, 0x180000
	v_exp_f32_e32 v14, v14
	s_addc_u32 s101, s13, 0
	v_exp_f32_e32 v15, v15
	s_add_u32 s0, s14, 0x200
	s_addc_u32 s1, s15, 0
	global_load_dwordx4 v[80:83], v154, s[100:101] offset:2048
	global_load_dwordx4 v[96:99], v158, s[0:1]
	global_load_dwordx4 v[84:87], v155, s[100:101] offset:2048
	global_load_dwordx4 v[100:103], v159, s[0:1]
	global_load_dwordx4 v[88:91], v156, s[100:101] offset:2048
	global_load_dwordx4 v[104:107], v160, s[0:1]
	global_load_dwordx4 v[92:95], v157, s[100:101] offset:2048
	global_load_dwordx4 v[108:111], v161, s[0:1]
	s_and_b32 s0, s3, 0xff
	s_lshr_b32 s1, s0, 2
	s_and_b32 s0, s0, 3
	s_lshl_b32 s0, s0, 5
	s_lshr_b32 vcc_lo, s3, 12
	s_add_u32 s0, s0, vcc_lo
	s_sub_i32 vcc_lo, s0, 4
	s_max_i32 vcc_lo, vcc_lo, 0
	s_min_i32 vcc_lo, vcc_lo, 0x78
	s_lshl_b32 vcc_hi, s1, 13
	s_lshl_b32 m0, s1, 8
	s_add_u32 m0, m0, 0x8000
	s_mul_i32 m0, m0, 0x1800
	s_add_u32 s16, s4, m0
	s_addc_u32 s17, s5, 0
	s_lshl_b32 m0, s1, 19
	s_add_u32 s36, s8, m0
	s_addc_u32 s37, s9, 0
	s_lshl_b32 m0, s0, 6
	s_add_u32 m0, m0, vcc_hi
	s_lshl_b32 m0, m0, 11
	s_add_u32 s98, s10, m0
	s_addc_u32 s99, s11, 0
	ds_read_b128 v[112:115], v146 offset:0
	ds_read_b128 v[116:119], v146 offset:4096
	ds_read_b128 v[120:123], v146 offset:8192
	ds_read_b128 v[124:127], v146 offset:12288
	ds_read_b128 v[128:131], v147 offset:0
	ds_read_b128 v[132:135], v147 offset:4096
	ds_read_b128 v[136:139], v147 offset:8192
	ds_read_b128 v[140:143], v147 offset:12288
	v_mov_b32_e32 v221, v220
	v_pk_add_f32 v[222:223], v[0:1], v[2:3]
	v_pk_add_f32 v[222:223], v[222:223], v[4:5]
	v_pk_add_f32 v[222:223], v[222:223], v[6:7]
	v_pk_add_f32 v[222:223], v[222:223], v[8:9]
	v_pk_add_f32 v[222:223], v[222:223], v[10:11]
	v_pk_add_f32 v[222:223], v[222:223], v[12:13]
	v_pk_add_f32 v[222:223], v[222:223], v[14:15]
	v_pk_mul_f32 v[32:33], v[32:33], v[220:221]
	v_pk_mul_f32 v[34:35], v[34:35], v[220:221]
	v_pk_mul_f32 v[36:37], v[36:37], v[220:221]
	v_pk_mul_f32 v[38:39], v[38:39], v[220:221]
	v_pk_mul_f32 v[40:41], v[40:41], v[220:221]
	v_pk_mul_f32 v[42:43], v[42:43], v[220:221]
	v_pk_mul_f32 v[44:45], v[44:45], v[220:221]
	v_pk_mul_f32 v[46:47], v[46:47], v[220:221]
	v_add_f32_e32 v203, v222, v223
	v_fma_f32 v201, v201, v220, v203
	v_cvt_pk_bf16_f32 v48, v0, v1
	v_cvt_pk_bf16_f32 v49, v2, v3
	v_cvt_pk_bf16_f32 v50, v4, v5
	v_cvt_pk_bf16_f32 v51, v6, v7
	v_cvt_pk_bf16_f32 v52, v8, v9
	v_cvt_pk_bf16_f32 v53, v10, v11
	v_cvt_pk_bf16_f32 v54, v12, v13
	v_cvt_pk_bf16_f32 v55, v14, v15
	s_waitcnt lgkmcnt(7)
	v_mfma_f32_16x16x32_bf16 v[32:35], v[112:115], v[48:51], v[32:35]
	s_waitcnt lgkmcnt(6)
	v_mfma_f32_16x16x32_bf16 v[36:39], v[116:119], v[48:51], v[36:39]
	s_waitcnt lgkmcnt(5)
	v_mfma_f32_16x16x32_bf16 v[40:43], v[120:123], v[48:51], v[40:43]
	s_waitcnt lgkmcnt(4)
	v_mfma_f32_16x16x32_bf16 v[44:47], v[124:127], v[48:51], v[44:47]
	s_waitcnt lgkmcnt(3)
	v_mfma_f32_16x16x32_bf16 v[32:35], v[128:131], v[52:55], v[32:35]
	s_waitcnt lgkmcnt(2)
	v_mfma_f32_16x16x32_bf16 v[36:39], v[132:135], v[52:55], v[36:39]
	s_waitcnt lgkmcnt(1)
	v_mfma_f32_16x16x32_bf16 v[40:43], v[136:139], v[52:55], v[40:43]
	s_waitcnt lgkmcnt(0)
	v_mfma_f32_16x16x32_bf16 v[44:47], v[140:143], v[52:55], v[44:47]
	ds_read_b32 v0, v184 offset:640
	ds_read_b32 v1, v185 offset:640
	ds_read_b32 v2, v186 offset:640
	ds_read_b32 v3, v187 offset:640
	ds_read_b32 v4, v184 offset:768
	ds_read_b32 v5, v185 offset:768
	ds_read_b32 v6, v186 offset:768
	ds_read_b32 v7, v187 offset:768
	ds_read_b32 v8, v188 offset:640
	ds_read_b32 v9, v189 offset:640
	ds_read_b32 v10, v190 offset:640
	ds_read_b32 v11, v191 offset:640
	ds_read_b32 v12, v188 offset:768
	ds_read_b32 v13, v189 offset:768
	ds_read_b32 v14, v190 offset:768
	ds_read_b32 v15, v191 offset:768
	s_barrier
; __device__ __forceinline__ void attn_phase(const Params& P, char* smem_raw) {
;     ...
;       __syncthreads();
;       f32x4 sacc[8];
; #pragma unroll
;       for (int t8 = 0; t8 < 8; ++t8) sacc[t8] = f32x4{0.f, 0.f, 0.f, 0.f};
; #pragma unroll
;       for (int s = 0; s < 2; ++s)
; #pragma unroll
;         for (int t8 = 0; t8 < 8; ++t8) {
;           const bf16x8 kf = *reinterpret_cast<const bf16x8*>(&sm_k[(t8 * 16 + (lane_c & 15)) * LDSS + s * 32 + (lane_c >> 4) * 8]);
;           sacc[t8] = __builtin_amdgcn_mfma_f32_16x16x32_bf16(qf[s], kf, sacc[t8], 0, 0, 0);
;         }
;       if (ck < 5) {
;         ATT_ISSUE(t, ck + 1)
;       } else if (t + VGRID < 8192) {
;         ATT_ISSUE(t + VGRID, 0)
;         ATT_QLOAD(t + VGRID)
;       }
;       if (ck < 4) {
;         const float* rb0 = sm_rpb + (rs + ck * 2 - r + 7) * 31;
; #pragma unroll
;         for (int t8 = 0; t8 < 8; ++t8)
; #pragma unroll
;           for (int reg = 0; reg < 4; ++reg)
;             sacc[t8][reg] += rb0[(t8 >> 2) * 31 + dco[reg][t8 & 3]];
;       }
; #pragma unroll
;       for (int reg = 0; reg < 4; ++reg) {
;         float mx = sacc[0][reg];
; #pragma unroll
;         for (int t8 = 1; t8 < 8; ++t8) mx = fmaxf(mx, sacc[t8][reg]);
;         mx = row16_max(mx);
;         const float mnew = fmaxf(mrow[reg], mx);
;         const float alpha = __builtin_amdgcn_exp2f(mrow[reg] - mnew);
;         mrow[reg] = mnew;
;         float rsum = 0.f;
; #pragma unroll
;         for (int t8 = 0; t8 < 8; ++t8) {
;           const float p = __builtin_amdgcn_exp2f(sacc[t8][reg] - mnew);
;           rsum += p;
;           sm_p[(wid * 16 + (lane_c >> 4) * 4 + reg) * 136 + t8 * 16 + (lane_c & 15)] = f2bf(p);
;         }
;         rsum = row16_sum(rsum);
;         lrow[reg] = lrow[reg] * alpha + rsum;
; #pragma unroll
;         for (int td = 0; td < 4; ++td) o[td][reg] *= alpha;
;       }
;       asm volatile("s_waitcnt lgkmcnt(0)" ::: "memory");
; #pragma unroll
;       for (int s4 = 0; s4 < 4; ++s4) {
;         const bf16x8 pf = *reinterpret_cast<const bf16x8*>(&sm_p[(wid * 16 + (lane_c & 15)) * 136 + s4 * 32 + (lane_c >> 4) * 8]);
; #pragma unroll
;         for (int td = 0; td < 4; ++td) {
;           const bf16x8 vf = *reinterpret_cast<const bf16x8*>(&sm_vt[(td * 16 + (lane_c & 15)) * 136 + s4 * 32 + (lane_c >> 4) * 8]);
;           o[td] = __builtin_amdgcn_mfma_f32_16x16x32_bf16(pf, vf, o[td], 0, 0, 0);
	ds_read_b128 v[112:115], v144 offset:32768
	ds_read_b128 v[116:119], v145 offset:32768
	ds_read_b128 v[120:123], v144 offset:40960
	ds_read_b128 v[124:127], v145 offset:40960
	ds_read_b128 v[128:131], v144 offset:34816
	ds_read_b128 v[132:135], v145 offset:34816
	ds_read_b128 v[136:139], v144 offset:43008
	ds_read_b128 v[140:143], v145 offset:43008
	s_waitcnt lgkmcnt(7)
	v_mfma_f32_16x16x32_bf16 v[0:3], v[112:115], v[64:67], v[0:3]
	s_waitcnt lgkmcnt(6)
	v_mfma_f32_16x16x32_bf16 v[0:3], v[116:119], v[68:71], v[0:3]
	s_waitcnt lgkmcnt(5)
	v_mfma_f32_16x16x32_bf16 v[4:7], v[120:123], v[64:67], v[4:7]
	s_waitcnt lgkmcnt(4)
	v_mfma_f32_16x16x32_bf16 v[4:7], v[124:127], v[68:71], v[4:7]
	s_waitcnt lgkmcnt(3)
	v_mfma_f32_16x16x32_bf16 v[8:11], v[128:131], v[64:67], v[8:11]
	s_waitcnt lgkmcnt(2)
	v_mfma_f32_16x16x32_bf16 v[8:11], v[132:135], v[68:71], v[8:11]
	s_waitcnt lgkmcnt(1)
	v_mfma_f32_16x16x32_bf16 v[12:15], v[136:139], v[64:67], v[12:15]
	s_waitcnt lgkmcnt(0)
	v_mfma_f32_16x16x32_bf16 v[12:15], v[140:143], v[68:71], v[12:15]
	s_nop 7
	v_max3_f32 v203, v0, v1, v2
	v_max3_f32 v203, v203, v3, v4
	v_max3_f32 v203, v203, v5, v6
	v_max3_f32 v203, v203, v7, v8
	v_max3_f32 v203, v203, v9, v10
	v_max3_f32 v203, v203, v11, v12
	v_max3_f32 v203, v203, v13, v14
	v_max_f32_e32 v203, v203, v15
	v_mov_b32_e32 v205, v203
	s_nop 1
	v_permlane16_swap_b32_e32 v203, v205
	v_max_f32_e32 v203, v203, v205
	v_mov_b32_e32 v205, v203
	s_nop 1
	v_permlane32_swap_b32_e32 v203, v205
	v_max_f32_e32 v203, v203, v205
	v_max_f32_e32 v218, v200, v203
	v_sub_f32_e32 v220, v200, v218
	v_mov_b32_e32 v219, v218
	v_exp_f32_e32 v220, v220
	v_mov_b32_e32 v200, v218
	v_pk_add_f32 v[0:1], v[0:1], v[218:219] neg_lo:[0,1] neg_hi:[0,1]
	v_pk_add_f32 v[2:3], v[2:3], v[218:219] neg_lo:[0,1] neg_hi:[0,1]
	v_pk_add_f32 v[4:5], v[4:5], v[218:219] neg_lo:[0,1] neg_hi:[0,1]
	v_pk_add_f32 v[6:7], v[6:7], v[218:219] neg_lo:[0,1] neg_hi:[0,1]
	v_pk_add_f32 v[8:9], v[8:9], v[218:219] neg_lo:[0,1] neg_hi:[0,1]
	v_pk_add_f32 v[10:11], v[10:11], v[218:219] neg_lo:[0,1] neg_hi:[0,1]
	v_pk_add_f32 v[12:13], v[12:13], v[218:219] neg_lo:[0,1] neg_hi:[0,1]
	v_pk_add_f32 v[14:15], v[14:15], v[218:219] neg_lo:[0,1] neg_hi:[0,1]
	v_exp_f32_e32 v0, v0
	s_waitcnt vmcnt(0)
	v_exp_f32_e32 v1, v1
	ds_write_b128 v150, v[80:83] offset:0
	v_exp_f32_e32 v2, v2
	ds_write_b128 v150, v[84:87] offset:4096
	v_exp_f32_e32 v3, v3
	ds_write_b128 v150, v[88:91] offset:8192
	v_exp_f32_e32 v4, v4
	ds_write_b128 v150, v[92:95] offset:12288
	v_exp_f32_e32 v5, v5
	ds_write_b64 v151, v[96:97] offset:0
	v_exp_f32_e32 v6, v6
	ds_write_b64 v229, v[98:99] offset:0
	v_exp_f32_e32 v7, v7
	ds_write_b64 v151, v[100:101] offset:4096
	v_exp_f32_e32 v8, v8
	ds_write_b64 v229, v[102:103] offset:4096
	v_exp_f32_e32 v9, v9
	ds_write_b64 v151, v[104:105] offset:8192
	v_exp_f32_e32 v10, v10
	ds_write_b64 v229, v[106:107] offset:8192
	v_exp_f32_e32 v11, v11
	ds_write_b64 v151, v[108:109] offset:12288
	v_exp_f32_e32 v12, v12
	ds_write_b64 v229, v[110:111] offset:12288
	v_exp_f32_e32 v13, v13
	s_add_u32 s100, s12, 0x240000
	v_exp_f32_e32 v14, v14
	s_addc_u32 s101, s13, 0
	v_exp_f32_e32 v15, v15
	s_add_u32 s0, s14, 0x300
	s_addc_u32 s1, s15, 0
	global_load_dwordx4 v[80:83], v154, s[100:101] offset:2048
	global_load_dwordx4 v[96:99], v158, s[0:1]
	global_load_dwordx4 v[84:87], v155, s[100:101] offset:2048
	global_load_dwordx4 v[100:103], v159, s[0:1]
	global_load_dwordx4 v[88:91], v156, s[100:101] offset:2048
	global_load_dwordx4 v[104:107], v160, s[0:1]
	global_load_dwordx4 v[92:95], v157, s[100:101] offset:2048
	global_load_dwordx4 v[108:111], v161, s[0:1]
	ds_read_b128 v[112:115], v146 offset:32768
	ds_read_b128 v[116:119], v146 offset:36864
	ds_read_b128 v[120:123], v146 offset:40960
	ds_read_b128 v[124:127], v146 offset:45056
	ds_read_b128 v[128:131], v147 offset:32768
	ds_read_b128 v[132:135], v147 offset:36864
	ds_read_b128 v[136:139], v147 offset:40960
	ds_read_b128 v[140:143], v147 offset:45056
	v_mov_b32_e32 v221, v220
	v_pk_add_f32 v[222:223], v[0:1], v[2:3]
	v_pk_add_f32 v[222:223], v[222:223], v[4:5]
	v_pk_add_f32 v[222:223], v[222:223], v[6:7]
	v_pk_add_f32 v[222:223], v[222:223], v[8:9]
	v_pk_add_f32 v[222:223], v[222:223], v[10:11]
	v_pk_add_f32 v[222:223], v[222:223], v[12:13]
	v_pk_add_f32 v[222:223], v[222:223], v[14:15]
	v_pk_mul_f32 v[32:33], v[32:33], v[220:221]
	v_pk_mul_f32 v[34:35], v[34:35], v[220:221]
	v_pk_mul_f32 v[36:37], v[36:37], v[220:221]
	v_pk_mul_f32 v[38:39], v[38:39], v[220:221]
	v_pk_mul_f32 v[40:41], v[40:41], v[220:221]
	v_pk_mul_f32 v[42:43], v[42:43], v[220:221]
	v_pk_mul_f32 v[44:45], v[44:45], v[220:221]
	v_pk_mul_f32 v[46:47], v[46:47], v[220:221]
	v_add_f32_e32 v203, v222, v223
	v_fma_f32 v201, v201, v220, v203
	v_cvt_pk_bf16_f32 v48, v0, v1
	v_cvt_pk_bf16_f32 v49, v2, v3
	v_cvt_pk_bf16_f32 v50, v4, v5
	v_cvt_pk_bf16_f32 v51, v6, v7
	v_cvt_pk_bf16_f32 v52, v8, v9
	v_cvt_pk_bf16_f32 v53, v10, v11
	v_cvt_pk_bf16_f32 v54, v12, v13
	v_cvt_pk_bf16_f32 v55, v14, v15
	s_waitcnt lgkmcnt(7)
	v_mfma_f32_16x16x32_bf16 v[32:35], v[112:115], v[48:51], v[32:35]
	s_waitcnt lgkmcnt(6)
	v_mfma_f32_16x16x32_bf16 v[36:39], v[116:119], v[48:51], v[36:39]
	s_waitcnt lgkmcnt(5)
	v_mfma_f32_16x16x32_bf16 v[40:43], v[120:123], v[48:51], v[40:43]
	s_waitcnt lgkmcnt(4)
	v_mfma_f32_16x16x32_bf16 v[44:47], v[124:127], v[48:51], v[44:47]
	s_waitcnt lgkmcnt(3)
	v_mfma_f32_16x16x32_bf16 v[32:35], v[128:131], v[52:55], v[32:35]
	s_waitcnt lgkmcnt(2)
	v_mfma_f32_16x16x32_bf16 v[36:39], v[132:135], v[52:55], v[36:39]
	s_waitcnt lgkmcnt(1)
	v_mfma_f32_16x16x32_bf16 v[40:43], v[136:139], v[52:55], v[40:43]
	s_waitcnt lgkmcnt(0)
	v_mfma_f32_16x16x32_bf16 v[44:47], v[140:143], v[52:55], v[44:47]
	ds_read_b32 v0, v184 offset:896
	ds_read_b32 v1, v185 offset:896
	ds_read_b32 v2, v186 offset:896
	ds_read_b32 v3, v187 offset:896
	ds_read_b32 v4, v184 offset:1024
	ds_read_b32 v5, v185 offset:1024
	ds_read_b32 v6, v186 offset:1024
	ds_read_b32 v7, v187 offset:1024
	ds_read_b32 v8, v188 offset:896
	ds_read_b32 v9, v189 offset:896
	ds_read_b32 v10, v190 offset:896
	ds_read_b32 v11, v191 offset:896
	ds_read_b32 v12, v188 offset:1024
	ds_read_b32 v13, v189 offset:1024
	ds_read_b32 v14, v190 offset:1024
	ds_read_b32 v15, v191 offset:1024
	s_barrier
; __device__ __forceinline__ void attn_phase(const Params& P, char* smem_raw) {
;     ...
;       __syncthreads();
;       f32x4 sacc[8];
; #pragma unroll
;       for (int t8 = 0; t8 < 8; ++t8) sacc[t8] = f32x4{0.f, 0.f, 0.f, 0.f};
; #pragma unroll
;       for (int s = 0; s < 2; ++s)
; #pragma unroll
;         for (int t8 = 0; t8 < 8; ++t8) {
;           const bf16x8 kf = *reinterpret_cast<const bf16x8*>(&sm_k[(t8 * 16 + (lane_c & 15)) * LDSS + s * 32 + (lane_c >> 4) * 8]);
;           sacc[t8] = __builtin_amdgcn_mfma_f32_16x16x32_bf16(qf[s], kf, sacc[t8], 0, 0, 0);
;         }
;       if (ck < 5) {
;         ATT_ISSUE(t, ck + 1)
;       } else if (t + VGRID < 8192) {
;         ATT_ISSUE(t + VGRID, 0)
;         ATT_QLOAD(t + VGRID)
;       }
;       if (ck < 4) {
;         const float* rb0 = sm_rpb + (rs + ck * 2 - r + 7) * 31;
; #pragma unroll
;         for (int t8 = 0; t8 < 8; ++t8)
; #pragma unroll
;           for (int reg = 0; reg < 4; ++reg)
;             sacc[t8][reg] += rb0[(t8 >> 2) * 31 + dco[reg][t8 & 3]];
;       }
; #pragma unroll
;       for (int reg = 0; reg < 4; ++reg) {
;         float mx = sacc[0][reg];
; #pragma unroll
;         for (int t8 = 1; t8 < 8; ++t8) mx = fmaxf(mx, sacc[t8][reg]);
;         mx = row16_max(mx);
;         const float mnew = fmaxf(mrow[reg], mx);
;         const float alpha = __builtin_amdgcn_exp2f(mrow[reg] - mnew);
;         mrow[reg] = mnew;
;         float rsum = 0.f;
; #pragma unroll
;         for (int t8 = 0; t8 < 8; ++t8) {
;           const float p = __builtin_amdgcn_exp2f(sacc[t8][reg] - mnew);
;           rsum += p;
;           sm_p[(wid * 16 + (lane_c >> 4) * 4 + reg) * 136 + t8 * 16 + (lane_c & 15)] = f2bf(p);
;         }
;         rsum = row16_sum(rsum);
;         lrow[reg] = lrow[reg] * alpha + rsum;
; #pragma unroll
;         for (int td = 0; td < 4; ++td) o[td][reg] *= alpha;
;       }
;       asm volatile("s_waitcnt lgkmcnt(0)" ::: "memory");
; #pragma unroll
;       for (int s4 = 0; s4 < 4; ++s4) {
;         const bf16x8 pf = *reinterpret_cast<const bf16x8*>(&sm_p[(wid * 16 + (lane_c & 15)) * 136 + s4 * 32 + (lane_c >> 4) * 8]);
; #pragma unroll
;         for (int td = 0; td < 4; ++td) {
;           const bf16x8 vf = *reinterpret_cast<const bf16x8*>(&sm_vt[(td * 16 + (lane_c & 15)) * 136 + s4 * 32 + (lane_c >> 4) * 8]);
;           o[td] = __builtin_amdgcn_mfma_f32_16x16x32_bf16(pf, vf, o[td], 0, 0, 0);
	ds_read_b128 v[112:115], v144 offset:0
	ds_read_b128 v[116:119], v145 offset:0
	ds_read_b128 v[120:123], v144 offset:8192
	ds_read_b128 v[124:127], v145 offset:8192
	ds_read_b128 v[128:131], v144 offset:2048
	ds_read_b128 v[132:135], v145 offset:2048
	ds_read_b128 v[136:139], v144 offset:10240
	ds_read_b128 v[140:143], v145 offset:10240
	s_waitcnt lgkmcnt(7)
	v_mfma_f32_16x16x32_bf16 v[0:3], v[112:115], v[64:67], v[0:3]
	s_waitcnt lgkmcnt(6)
	v_mfma_f32_16x16x32_bf16 v[0:3], v[116:119], v[68:71], v[0:3]
	s_waitcnt lgkmcnt(5)
	v_mfma_f32_16x16x32_bf16 v[4:7], v[120:123], v[64:67], v[4:7]
	s_waitcnt lgkmcnt(4)
	v_mfma_f32_16x16x32_bf16 v[4:7], v[124:127], v[68:71], v[4:7]
	s_waitcnt lgkmcnt(3)
	v_mfma_f32_16x16x32_bf16 v[8:11], v[128:131], v[64:67], v[8:11]
	s_waitcnt lgkmcnt(2)
	v_mfma_f32_16x16x32_bf16 v[8:11], v[132:135], v[68:71], v[8:11]
	s_waitcnt lgkmcnt(1)
	v_mfma_f32_16x16x32_bf16 v[12:15], v[136:139], v[64:67], v[12:15]
	s_waitcnt lgkmcnt(0)
	v_mfma_f32_16x16x32_bf16 v[12:15], v[140:143], v[68:71], v[12:15]
	s_nop 7
	v_max3_f32 v203, v0, v1, v2
	v_max3_f32 v203, v203, v3, v4
	v_max3_f32 v203, v203, v5, v6
	v_max3_f32 v203, v203, v7, v8
	v_max3_f32 v203, v203, v9, v10
	v_max3_f32 v203, v203, v11, v12
	v_max3_f32 v203, v203, v13, v14
	v_max_f32_e32 v203, v203, v15
	v_mov_b32_e32 v205, v203
	s_nop 1
	v_permlane16_swap_b32_e32 v203, v205
	v_max_f32_e32 v203, v203, v205
	v_mov_b32_e32 v205, v203
	s_nop 1
	v_permlane32_swap_b32_e32 v203, v205
	v_max_f32_e32 v203, v203, v205
	v_max_f32_e32 v218, v200, v203
	v_sub_f32_e32 v220, v200, v218
	v_mov_b32_e32 v219, v218
	v_exp_f32_e32 v220, v220
	v_mov_b32_e32 v200, v218
	v_pk_add_f32 v[0:1], v[0:1], v[218:219] neg_lo:[0,1] neg_hi:[0,1]
	v_pk_add_f32 v[2:3], v[2:3], v[218:219] neg_lo:[0,1] neg_hi:[0,1]
	v_pk_add_f32 v[4:5], v[4:5], v[218:219] neg_lo:[0,1] neg_hi:[0,1]
	v_pk_add_f32 v[6:7], v[6:7], v[218:219] neg_lo:[0,1] neg_hi:[0,1]
	v_pk_add_f32 v[8:9], v[8:9], v[218:219] neg_lo:[0,1] neg_hi:[0,1]
	v_pk_add_f32 v[10:11], v[10:11], v[218:219] neg_lo:[0,1] neg_hi:[0,1]
	v_pk_add_f32 v[12:13], v[12:13], v[218:219] neg_lo:[0,1] neg_hi:[0,1]
	v_pk_add_f32 v[14:15], v[14:15], v[218:219] neg_lo:[0,1] neg_hi:[0,1]
	v_exp_f32_e32 v0, v0
	s_waitcnt vmcnt(0)
	v_exp_f32_e32 v1, v1
	ds_write_b128 v150, v[80:83] offset:32768
	v_exp_f32_e32 v2, v2
	ds_write_b128 v150, v[84:87] offset:36864
	v_exp_f32_e32 v3, v3
	ds_write_b128 v150, v[88:91] offset:40960
	v_exp_f32_e32 v4, v4
	ds_write_b128 v150, v[92:95] offset:45056
	v_exp_f32_e32 v5, v5
	ds_write_b64 v151, v[96:97] offset:32768
	v_exp_f32_e32 v6, v6
	ds_write_b64 v229, v[98:99] offset:32768
	v_exp_f32_e32 v7, v7
	ds_write_b64 v151, v[100:101] offset:36864
	v_exp_f32_e32 v8, v8
	ds_write_b64 v229, v[102:103] offset:36864
	v_exp_f32_e32 v9, v9
	ds_write_b64 v151, v[104:105] offset:40960
	v_exp_f32_e32 v10, v10
	ds_write_b64 v229, v[106:107] offset:40960
	v_exp_f32_e32 v11, v11
	ds_write_b64 v151, v[108:109] offset:45056
	v_exp_f32_e32 v12, v12
	ds_write_b64 v229, v[110:111] offset:45056
	v_exp_f32_e32 v13, v13
	s_add_u32 s100, s16, 0x0
	v_exp_f32_e32 v14, v14
	s_addc_u32 s101, s17, 0
	v_exp_f32_e32 v15, v15
	s_add_u32 s0, s36, 0x0
	s_addc_u32 s1, s37, 0
	global_load_dwordx4 v[80:83], v154, s[100:101] offset:2048
	global_load_dwordx4 v[96:99], v162, s[0:1]
	global_load_dwordx4 v[84:87], v155, s[100:101] offset:2048
	global_load_dwordx4 v[100:103], v163, s[0:1]
	global_load_dwordx4 v[88:91], v156, s[100:101] offset:2048
	global_load_dwordx4 v[104:107], v164, s[0:1]
	global_load_dwordx4 v[92:95], v157, s[100:101] offset:2048
	global_load_dwordx4 v[108:111], v165, s[0:1]
	ds_read_b128 v[112:115], v146 offset:0
	ds_read_b128 v[116:119], v146 offset:4096
	ds_read_b128 v[120:123], v146 offset:8192
	ds_read_b128 v[124:127], v146 offset:12288
	ds_read_b128 v[128:131], v147 offset:0
	ds_read_b128 v[132:135], v147 offset:4096
	ds_read_b128 v[136:139], v147 offset:8192
	ds_read_b128 v[140:143], v147 offset:12288
	v_mov_b32_e32 v221, v220
	v_pk_add_f32 v[222:223], v[0:1], v[2:3]
	v_pk_add_f32 v[222:223], v[222:223], v[4:5]
	v_pk_add_f32 v[222:223], v[222:223], v[6:7]
	v_pk_add_f32 v[222:223], v[222:223], v[8:9]
	v_pk_add_f32 v[222:223], v[222:223], v[10:11]
	v_pk_add_f32 v[222:223], v[222:223], v[12:13]
	v_pk_add_f32 v[222:223], v[222:223], v[14:15]
	v_pk_mul_f32 v[32:33], v[32:33], v[220:221]
	v_pk_mul_f32 v[34:35], v[34:35], v[220:221]
	v_pk_mul_f32 v[36:37], v[36:37], v[220:221]
	v_pk_mul_f32 v[38:39], v[38:39], v[220:221]
	v_pk_mul_f32 v[40:41], v[40:41], v[220:221]
	v_pk_mul_f32 v[42:43], v[42:43], v[220:221]
	v_pk_mul_f32 v[44:45], v[44:45], v[220:221]
	v_pk_mul_f32 v[46:47], v[46:47], v[220:221]
	v_add_f32_e32 v203, v222, v223
	v_fma_f32 v201, v201, v220, v203
	v_cvt_pk_bf16_f32 v48, v0, v1
	v_cvt_pk_bf16_f32 v49, v2, v3
	v_cvt_pk_bf16_f32 v50, v4, v5
	v_cvt_pk_bf16_f32 v51, v6, v7
	v_cvt_pk_bf16_f32 v52, v8, v9
	v_cvt_pk_bf16_f32 v53, v10, v11
	v_cvt_pk_bf16_f32 v54, v12, v13
	v_cvt_pk_bf16_f32 v55, v14, v15
	s_waitcnt lgkmcnt(7)
	v_mfma_f32_16x16x32_bf16 v[32:35], v[112:115], v[48:51], v[32:35]
	s_waitcnt lgkmcnt(6)
	v_mfma_f32_16x16x32_bf16 v[36:39], v[116:119], v[48:51], v[36:39]
	s_waitcnt lgkmcnt(5)
	v_mfma_f32_16x16x32_bf16 v[40:43], v[120:123], v[48:51], v[40:43]
	s_waitcnt lgkmcnt(4)
	v_mfma_f32_16x16x32_bf16 v[44:47], v[124:127], v[48:51], v[44:47]
	s_waitcnt lgkmcnt(3)
	v_mfma_f32_16x16x32_bf16 v[32:35], v[128:131], v[52:55], v[32:35]
	s_waitcnt lgkmcnt(2)
	v_mfma_f32_16x16x32_bf16 v[36:39], v[132:135], v[52:55], v[36:39]
	s_waitcnt lgkmcnt(1)
	v_mfma_f32_16x16x32_bf16 v[40:43], v[136:139], v[52:55], v[40:43]
	s_waitcnt lgkmcnt(0)
	v_mfma_f32_16x16x32_bf16 v[44:47], v[140:143], v[52:55], v[44:47]
	ds_read_b32 v0, v184 offset:1152
	ds_read_b32 v1, v185 offset:1152
	ds_read_b32 v2, v186 offset:1152
	ds_read_b32 v3, v187 offset:1152
	ds_read_b32 v4, v184 offset:1280
	ds_read_b32 v5, v185 offset:1280
	ds_read_b32 v6, v186 offset:1280
	ds_read_b32 v7, v187 offset:1280
	ds_read_b32 v8, v188 offset:1152
	ds_read_b32 v9, v189 offset:1152
	ds_read_b32 v10, v190 offset:1152
	ds_read_b32 v11, v191 offset:1152
	ds_read_b32 v12, v188 offset:1280
	ds_read_b32 v13, v189 offset:1280
	ds_read_b32 v14, v190 offset:1280
	ds_read_b32 v15, v191 offset:1280
	s_barrier
; __device__ __forceinline__ void attn_phase(const Params& P, char* smem_raw) {
;     ...
;       __syncthreads();
;       f32x4 sacc[8];
; #pragma unroll
;       for (int t8 = 0; t8 < 8; ++t8) sacc[t8] = f32x4{0.f, 0.f, 0.f, 0.f};
; #pragma unroll
;       for (int s = 0; s < 2; ++s)
; #pragma unroll
;         for (int t8 = 0; t8 < 8; ++t8) {
;           const bf16x8 kf = *reinterpret_cast<const bf16x8*>(&sm_k[(t8 * 16 + (lane_c & 15)) * LDSS + s * 32 + (lane_c >> 4) * 8]);
;           sacc[t8] = __builtin_amdgcn_mfma_f32_16x16x32_bf16(qf[s], kf, sacc[t8], 0, 0, 0);
;         }
;       if (ck < 5) {
;         ATT_ISSUE(t, ck + 1)
;       } else if (t + VGRID < 8192) {
;         ATT_ISSUE(t + VGRID, 0)
;         ATT_QLOAD(t + VGRID)
;       }
;       if (ck < 4) {
;         const float* rb0 = sm_rpb + (rs + ck * 2 - r + 7) * 31;
; #pragma unroll
;         for (int t8 = 0; t8 < 8; ++t8)
; #pragma unroll
;           for (int reg = 0; reg < 4; ++reg)
;             sacc[t8][reg] += rb0[(t8 >> 2) * 31 + dco[reg][t8 & 3]];
;       }
; #pragma unroll
;       for (int reg = 0; reg < 4; ++reg) {
;         float mx = sacc[0][reg];
; #pragma unroll
;         for (int t8 = 1; t8 < 8; ++t8) mx = fmaxf(mx, sacc[t8][reg]);
;         mx = row16_max(mx);
;         const float mnew = fmaxf(mrow[reg], mx);
;         const float alpha = __builtin_amdgcn_exp2f(mrow[reg] - mnew);
;         mrow[reg] = mnew;
;         float rsum = 0.f;
; #pragma unroll
;         for (int t8 = 0; t8 < 8; ++t8) {
;           const float p = __builtin_amdgcn_exp2f(sacc[t8][reg] - mnew);
;           rsum += p;
;           sm_p[(wid * 16 + (lane_c >> 4) * 4 + reg) * 136 + t8 * 16 + (lane_c & 15)] = f2bf(p);
;         }
;         rsum = row16_sum(rsum);
;         lrow[reg] = lrow[reg] * alpha + rsum;
; #pragma unroll
;         for (int td = 0; td < 4; ++td) o[td][reg] *= alpha;
;       }
;       asm volatile("s_waitcnt lgkmcnt(0)" ::: "memory");
; #pragma unroll
;       for (int s4 = 0; s4 < 4; ++s4) {
;         const bf16x8 pf = *reinterpret_cast<const bf16x8*>(&sm_p[(wid * 16 + (lane_c & 15)) * 136 + s4 * 32 + (lane_c >> 4) * 8]);
; #pragma unroll
;         for (int td = 0; td < 4; ++td) {
;           const bf16x8 vf = *reinterpret_cast<const bf16x8*>(&sm_vt[(td * 16 + (lane_c & 15)) * 136 + s4 * 32 + (lane_c >> 4) * 8]);
;           o[td] = __builtin_amdgcn_mfma_f32_16x16x32_bf16(pf, vf, o[td], 0, 0, 0);
	ds_read_b128 v[112:115], v144 offset:32768
	ds_read_b128 v[116:119], v145 offset:32768
	ds_read_b128 v[120:123], v144 offset:40960
	ds_read_b128 v[124:127], v145 offset:40960
	ds_read_b128 v[128:131], v144 offset:34816
	ds_read_b128 v[132:135], v145 offset:34816
	ds_read_b128 v[136:139], v144 offset:43008
	ds_read_b128 v[140:143], v145 offset:43008
	s_waitcnt lgkmcnt(7)
	v_mfma_f32_16x16x32_bf16 v[0:3], v[112:115], v[64:67], v[0:3]
	s_waitcnt lgkmcnt(6)
	v_mfma_f32_16x16x32_bf16 v[0:3], v[116:119], v[68:71], v[0:3]
	s_waitcnt lgkmcnt(5)
	v_mfma_f32_16x16x32_bf16 v[4:7], v[120:123], v[64:67], v[4:7]
	s_waitcnt lgkmcnt(4)
	v_mfma_f32_16x16x32_bf16 v[4:7], v[124:127], v[68:71], v[4:7]
	s_waitcnt lgkmcnt(3)
	v_mfma_f32_16x16x32_bf16 v[8:11], v[128:131], v[64:67], v[8:11]
	s_waitcnt lgkmcnt(2)
	v_mfma_f32_16x16x32_bf16 v[8:11], v[132:135], v[68:71], v[8:11]
	s_waitcnt lgkmcnt(1)
	v_mfma_f32_16x16x32_bf16 v[12:15], v[136:139], v[64:67], v[12:15]
	s_waitcnt lgkmcnt(0)
	v_mfma_f32_16x16x32_bf16 v[12:15], v[140:143], v[68:71], v[12:15]
	s_nop 7
	v_max3_f32 v203, v0, v1, v2
	v_max3_f32 v203, v203, v3, v4
	v_max3_f32 v203, v203, v5, v6
	v_max3_f32 v203, v203, v7, v8
	v_max3_f32 v203, v203, v9, v10
	v_max3_f32 v203, v203, v11, v12
	v_max3_f32 v203, v203, v13, v14
	v_max_f32_e32 v203, v203, v15
	v_mov_b32_e32 v205, v203
	s_nop 1
	v_permlane16_swap_b32_e32 v203, v205
	v_max_f32_e32 v203, v203, v205
	v_mov_b32_e32 v205, v203
	s_nop 1
	v_permlane32_swap_b32_e32 v203, v205
	v_max_f32_e32 v203, v203, v205
	v_max_f32_e32 v218, v200, v203
	v_sub_f32_e32 v220, v200, v218
	v_mov_b32_e32 v219, v218
	v_exp_f32_e32 v220, v220
	v_mov_b32_e32 v200, v218
	v_pk_add_f32 v[0:1], v[0:1], v[218:219] neg_lo:[0,1] neg_hi:[0,1]
	v_pk_add_f32 v[2:3], v[2:3], v[218:219] neg_lo:[0,1] neg_hi:[0,1]
	v_pk_add_f32 v[4:5], v[4:5], v[218:219] neg_lo:[0,1] neg_hi:[0,1]
	v_pk_add_f32 v[6:7], v[6:7], v[218:219] neg_lo:[0,1] neg_hi:[0,1]
	v_pk_add_f32 v[8:9], v[8:9], v[218:219] neg_lo:[0,1] neg_hi:[0,1]
	v_pk_add_f32 v[10:11], v[10:11], v[218:219] neg_lo:[0,1] neg_hi:[0,1]
	v_pk_add_f32 v[12:13], v[12:13], v[218:219] neg_lo:[0,1] neg_hi:[0,1]
	v_pk_add_f32 v[14:15], v[14:15], v[218:219] neg_lo:[0,1] neg_hi:[0,1]
	v_exp_f32_e32 v0, v0
	s_waitcnt vmcnt(0)
	v_exp_f32_e32 v1, v1
	ds_write_b128 v150, v[80:83] offset:0
	v_exp_f32_e32 v2, v2
	ds_write_b128 v150, v[84:87] offset:4096
	v_exp_f32_e32 v3, v3
	ds_write_b128 v150, v[88:91] offset:8192
	v_exp_f32_e32 v4, v4
	ds_write_b128 v150, v[92:95] offset:12288
	v_exp_f32_e32 v5, v5
	ds_write_b64 v151, v[96:97] offset:0
	v_exp_f32_e32 v6, v6
	ds_write_b64 v229, v[98:99] offset:0
	v_exp_f32_e32 v7, v7
	ds_write_b64 v151, v[100:101] offset:4096
	v_exp_f32_e32 v8, v8
	ds_write_b64 v229, v[102:103] offset:4096
	v_exp_f32_e32 v9, v9
	ds_write_b64 v151, v[104:105] offset:8192
	v_exp_f32_e32 v10, v10
	ds_write_b64 v229, v[106:107] offset:8192
	v_exp_f32_e32 v11, v11
	ds_write_b64 v151, v[108:109] offset:12288
	v_exp_f32_e32 v12, v12
	ds_write_b64 v229, v[110:111] offset:12288
	v_exp_f32_e32 v13, v13
	s_add_u32 s100, s16, 0xc0000
	v_exp_f32_e32 v14, v14
	s_addc_u32 s101, s17, 0
	v_exp_f32_e32 v15, v15
	s_add_u32 s0, s36, 0x100
	s_addc_u32 s1, s37, 0
	global_load_dwordx4 v[80:83], v154, s[100:101] offset:2048
	global_load_dwordx4 v[96:99], v162, s[0:1]
	global_load_dwordx4 v[84:87], v155, s[100:101] offset:2048
	global_load_dwordx4 v[100:103], v163, s[0:1]
	global_load_dwordx4 v[88:91], v156, s[100:101] offset:2048
	global_load_dwordx4 v[104:107], v164, s[0:1]
	global_load_dwordx4 v[92:95], v157, s[100:101] offset:2048
	global_load_dwordx4 v[108:111], v165, s[0:1]
	s_and_b32 s0, s3, 0xff
	s_add_u32 s0, s0, 1
	s_min_u32 s0, s0, 15
	s_lshr_b32 s1, s0, 2
	s_and_b32 s0, s0, 3
	s_lshl_b32 s0, s0, 5
	s_lshr_b32 vcc_lo, s3, 12
	s_add_u32 s0, s0, vcc_lo
	s_sub_i32 vcc_lo, s0, 4
	s_max_i32 vcc_lo, vcc_lo, 0
	s_min_i32 vcc_lo, vcc_lo, 0x78
	s_lshl_b32 vcc_hi, s1, 13
	s_lshl_b32 m0, vcc_lo, 6
	s_add_u32 m0, m0, vcc_hi
	s_mul_i32 m0, m0, 0x1800
	s_add_u32 s12, s4, m0
	s_addc_u32 s13, s5, 0
	s_lshl_b32 m0, s1, 24
	s_lshl_b32 s100, vcc_lo, 7
	s_add_u32 m0, m0, s100
	s_add_u32 s14, s6, m0
	s_addc_u32 s15, s7, 0
	s_lshl_b32 m0, s0, 6
	s_add_u32 m0, m0, vcc_hi
	s_mul_i32 m0, m0, 0x1800
	s_add_u32 s100, s4, m0
	s_addc_u32 s101, s5, 0
	global_load_dwordx4 v[72:75], v166, s[100:101]
	global_load_dwordx4 v[76:79], v166, s[100:101] offset:64
	ds_read_b128 v[112:115], v146 offset:32768
	ds_read_b128 v[116:119], v146 offset:36864
	ds_read_b128 v[120:123], v146 offset:40960
	ds_read_b128 v[124:127], v146 offset:45056
	ds_read_b128 v[128:131], v147 offset:32768
	ds_read_b128 v[132:135], v147 offset:36864
	ds_read_b128 v[136:139], v147 offset:40960
	ds_read_b128 v[140:143], v147 offset:45056
	v_mov_b32_e32 v221, v220
	v_pk_add_f32 v[222:223], v[0:1], v[2:3]
	v_pk_add_f32 v[222:223], v[222:223], v[4:5]
	v_pk_add_f32 v[222:223], v[222:223], v[6:7]
	v_pk_add_f32 v[222:223], v[222:223], v[8:9]
	v_pk_add_f32 v[222:223], v[222:223], v[10:11]
	v_pk_add_f32 v[222:223], v[222:223], v[12:13]
	v_pk_add_f32 v[222:223], v[222:223], v[14:15]
	v_pk_mul_f32 v[32:33], v[32:33], v[220:221]
	v_pk_mul_f32 v[34:35], v[34:35], v[220:221]
	v_pk_mul_f32 v[36:37], v[36:37], v[220:221]
	v_pk_mul_f32 v[38:39], v[38:39], v[220:221]
	v_pk_mul_f32 v[40:41], v[40:41], v[220:221]
	v_pk_mul_f32 v[42:43], v[42:43], v[220:221]
	v_pk_mul_f32 v[44:45], v[44:45], v[220:221]
	v_pk_mul_f32 v[46:47], v[46:47], v[220:221]
	v_add_f32_e32 v203, v222, v223
	v_fma_f32 v201, v201, v220, v203
	v_cvt_pk_bf16_f32 v48, v0, v1
	v_cvt_pk_bf16_f32 v49, v2, v3
	v_cvt_pk_bf16_f32 v50, v4, v5
	v_cvt_pk_bf16_f32 v51, v6, v7
	v_cvt_pk_bf16_f32 v52, v8, v9
	v_cvt_pk_bf16_f32 v53, v10, v11
	v_cvt_pk_bf16_f32 v54, v12, v13
	v_cvt_pk_bf16_f32 v55, v14, v15
	s_waitcnt lgkmcnt(7)
	v_mfma_f32_16x16x32_bf16 v[32:35], v[112:115], v[48:51], v[32:35]
	s_waitcnt lgkmcnt(6)
	v_mfma_f32_16x16x32_bf16 v[36:39], v[116:119], v[48:51], v[36:39]
	s_waitcnt lgkmcnt(5)
	v_mfma_f32_16x16x32_bf16 v[40:43], v[120:123], v[48:51], v[40:43]
	s_waitcnt lgkmcnt(4)
	v_mfma_f32_16x16x32_bf16 v[44:47], v[124:127], v[48:51], v[44:47]
	s_waitcnt lgkmcnt(3)
	v_mfma_f32_16x16x32_bf16 v[32:35], v[128:131], v[52:55], v[32:35]
	s_waitcnt lgkmcnt(2)
	v_mfma_f32_16x16x32_bf16 v[36:39], v[132:135], v[52:55], v[36:39]
	s_waitcnt lgkmcnt(1)
	v_mfma_f32_16x16x32_bf16 v[40:43], v[136:139], v[52:55], v[40:43]
	s_waitcnt lgkmcnt(0)
	v_mfma_f32_16x16x32_bf16 v[44:47], v[140:143], v[52:55], v[44:47]
	s_barrier
; __device__ __forceinline__ void attn_phase(const Params& P, char* smem_raw) {
;     ...
;       __syncthreads();
;       f32x4 sacc[8];
; #pragma unroll
;       for (int t8 = 0; t8 < 8; ++t8) sacc[t8] = f32x4{0.f, 0.f, 0.f, 0.f};
; #pragma unroll
;       for (int s = 0; s < 2; ++s)
; #pragma unroll
;         for (int t8 = 0; t8 < 8; ++t8) {
;           const bf16x8 kf = *reinterpret_cast<const bf16x8*>(&sm_k[(t8 * 16 + (lane_c & 15)) * LDSS + s * 32 + (lane_c >> 4) * 8]);
;           sacc[t8] = __builtin_amdgcn_mfma_f32_16x16x32_bf16(qf[s], kf, sacc[t8], 0, 0, 0);
;         }
;       if (ck < 5) {
;         ATT_ISSUE(t, ck + 1)
;       } else if (t + VGRID < 8192) {
;         ATT_ISSUE(t + VGRID, 0)
;         ATT_QLOAD(t + VGRID)
;       }
;       if (ck < 4) {
;         const float* rb0 = sm_rpb + (rs + ck * 2 - r + 7) * 31;
; #pragma unroll
;         for (int t8 = 0; t8 < 8; ++t8)
; #pragma unroll
;           for (int reg = 0; reg < 4; ++reg)
;             sacc[t8][reg] += rb0[(t8 >> 2) * 31 + dco[reg][t8 & 3]];
;       }
; #pragma unroll
;       for (int reg = 0; reg < 4; ++reg) {
;         float mx = sacc[0][reg];
; #pragma unroll
;         for (int t8 = 1; t8 < 8; ++t8) mx = fmaxf(mx, sacc[t8][reg]);
;         mx = row16_max(mx);
	ds_read_b128 v[112:115], v149 offset:0
	ds_read_b128 v[116:119], v224 offset:0
	ds_read_b128 v[120:123], v149 offset:8192
	ds_read_b128 v[124:127], v224 offset:8192
	ds_read_b128 v[128:131], v149 offset:2048
	ds_read_b128 v[132:135], v224 offset:2048
	ds_read_b128 v[136:139], v149 offset:10240
	ds_read_b128 v[140:143], v224 offset:10240
	s_waitcnt lgkmcnt(7)
	v_mfma_f32_16x16x32_bf16 v[0:3], v[112:115], v[64:67], 0
	ds_read_b128 v[112:115], v149 offset:4096
	s_waitcnt lgkmcnt(7)
	v_mfma_f32_16x16x32_bf16 v[0:3], v[116:119], v[68:71], v[0:3]
	ds_read_b128 v[116:119], v224 offset:4096
	s_waitcnt lgkmcnt(7)
	v_mfma_f32_16x16x32_bf16 v[4:7], v[120:123], v[64:67], 0
	ds_read_b128 v[120:123], v149 offset:12288
	s_waitcnt lgkmcnt(7)
	v_mfma_f32_16x16x32_bf16 v[4:7], v[124:127], v[68:71], v[4:7]
	ds_read_b128 v[124:127], v224 offset:12288
	s_waitcnt lgkmcnt(7)
	v_mfma_f32_16x16x32_bf16 v[8:11], v[128:131], v[64:67], 0
	ds_read_b128 v[128:131], v149 offset:6144
	s_waitcnt lgkmcnt(7)
	v_mfma_f32_16x16x32_bf16 v[8:11], v[132:135], v[68:71], v[8:11]
	ds_read_b128 v[132:135], v224 offset:6144
	s_waitcnt lgkmcnt(7)
	v_mfma_f32_16x16x32_bf16 v[12:15], v[136:139], v[64:67], 0
	ds_read_b128 v[136:139], v149 offset:14336
	s_waitcnt lgkmcnt(7)
	v_mfma_f32_16x16x32_bf16 v[12:15], v[140:143], v[68:71], v[12:15]
	ds_read_b128 v[140:143], v224 offset:14336
	s_waitcnt lgkmcnt(7)
	v_mfma_f32_16x16x32_bf16 v[16:19], v[112:115], v[64:67], 0
	s_waitcnt lgkmcnt(6)
	v_mfma_f32_16x16x32_bf16 v[16:19], v[116:119], v[68:71], v[16:19]
	s_waitcnt lgkmcnt(5)
	v_mfma_f32_16x16x32_bf16 v[20:23], v[120:123], v[64:67], 0
	s_waitcnt lgkmcnt(4)
	v_mfma_f32_16x16x32_bf16 v[20:23], v[124:127], v[68:71], v[20:23]
	s_waitcnt lgkmcnt(3)
	v_mfma_f32_16x16x32_bf16 v[24:27], v[128:131], v[64:67], 0
	s_waitcnt lgkmcnt(2)
	v_mfma_f32_16x16x32_bf16 v[24:27], v[132:135], v[68:71], v[24:27]
	s_waitcnt lgkmcnt(1)
	v_mfma_f32_16x16x32_bf16 v[28:31], v[136:139], v[64:67], 0
	s_waitcnt lgkmcnt(0)
	v_mfma_f32_16x16x32_bf16 v[28:31], v[140:143], v[68:71], v[28:31]
	s_nop 7
	v_max3_f32 v203, v0, v1, v2
	v_max3_f32 v203, v203, v3, v4
	v_max3_f32 v203, v203, v5, v6
	v_max3_f32 v203, v203, v7, v8
	v_max3_f32 v203, v203, v9, v10
	v_max3_f32 v203, v203, v11, v12
	v_max3_f32 v203, v203, v13, v14
	v_max3_f32 v203, v203, v15, v16
	v_max3_f32 v203, v203, v17, v18
	v_max3_f32 v203, v203, v19, v20
	v_max3_f32 v203, v203, v21, v22
	v_max3_f32 v203, v203, v23, v24
	v_max3_f32 v203, v203, v25, v26
	v_max3_f32 v203, v203, v27, v28
	v_max3_f32 v203, v203, v29, v30
	v_max_f32_e32 v203, v203, v31
	v_mov_b32_e32 v205, v203
	s_nop 1
	v_permlane16_swap_b32_e32 v203, v205
	v_max_f32_e32 v203, v203, v205
	v_mov_b32_e32 v205, v203
	s_nop 1
	v_permlane32_swap_b32_e32 v203, v205
	v_max_f32_e32 v203, v203, v205
	v_max_f32_e32 v218, v200, v203
	v_sub_f32_e32 v220, v200, v218
	v_mov_b32_e32 v219, v218
	v_exp_f32_e32 v220, v220
	v_mov_b32_e32 v200, v218
	v_pk_add_f32 v[0:1], v[0:1], v[218:219] neg_lo:[0,1] neg_hi:[0,1]
	v_pk_add_f32 v[2:3], v[2:3], v[218:219] neg_lo:[0,1] neg_hi:[0,1]
	v_pk_add_f32 v[4:5], v[4:5], v[218:219] neg_lo:[0,1] neg_hi:[0,1]
	v_pk_add_f32 v[6:7], v[6:7], v[218:219] neg_lo:[0,1] neg_hi:[0,1]
	v_pk_add_f32 v[8:9], v[8:9], v[218:219] neg_lo:[0,1] neg_hi:[0,1]
	v_pk_add_f32 v[10:11], v[10:11], v[218:219] neg_lo:[0,1] neg_hi:[0,1]
	v_pk_add_f32 v[12:13], v[12:13], v[218:219] neg_lo:[0,1] neg_hi:[0,1]
	v_pk_add_f32 v[14:15], v[14:15], v[218:219] neg_lo:[0,1] neg_hi:[0,1]
	v_pk_add_f32 v[16:17], v[16:17], v[218:219] neg_lo:[0,1] neg_hi:[0,1]
	v_pk_add_f32 v[18:19], v[18:19], v[218:219] neg_lo:[0,1] neg_hi:[0,1]
	v_pk_add_f32 v[20:21], v[20:21], v[218:219] neg_lo:[0,1] neg_hi:[0,1]
	v_pk_add_f32 v[22:23], v[22:23], v[218:219] neg_lo:[0,1] neg_hi:[0,1]
	v_pk_add_f32 v[24:25], v[24:25], v[218:219] neg_lo:[0,1] neg_hi:[0,1]
	v_pk_add_f32 v[26:27], v[26:27], v[218:219] neg_lo:[0,1] neg_hi:[0,1]
	v_pk_add_f32 v[28:29], v[28:29], v[218:219] neg_lo:[0,1] neg_hi:[0,1]
	v_pk_add_f32 v[30:31], v[30:31], v[218:219] neg_lo:[0,1] neg_hi:[0,1]
	v_exp_f32_e32 v0, v0
	s_waitcnt vmcnt(2)
	v_exp_f32_e32 v1, v1
	ds_write_b128 v150, v[80:83] offset:32768
	v_exp_f32_e32 v2, v2
	ds_write_b128 v150, v[84:87] offset:36864
	v_exp_f32_e32 v3, v3
	ds_write_b128 v150, v[88:91] offset:40960
	v_exp_f32_e32 v4, v4
	ds_write_b128 v150, v[92:95] offset:45056
	v_exp_f32_e32 v5, v5
	ds_write_b64 v151, v[96:97] offset:32768
	v_exp_f32_e32 v6, v6
	ds_write_b64 v229, v[98:99] offset:32768
	v_exp_f32_e32 v7, v7
	ds_write_b64 v151, v[100:101] offset:36864
	v_exp_f32_e32 v8, v8
	ds_write_b64 v229, v[102:103] offset:36864
	v_exp_f32_e32 v9, v9
	ds_write_b64 v151, v[104:105] offset:40960
	v_exp_f32_e32 v10, v10
	ds_write_b64 v229, v[106:107] offset:40960
	v_exp_f32_e32 v11, v11
	ds_write_b64 v151, v[108:109] offset:45056
	v_exp_f32_e32 v12, v12
	ds_write_b64 v229, v[110:111] offset:45056
	v_exp_f32_e32 v13, v13
	s_add_u32 s100, s12, 0x0
	v_exp_f32_e32 v14, v14
	s_addc_u32 s101, s13, 0
	v_exp_f32_e32 v15, v15
	s_add_u32 s0, s14, 0x0
	v_exp_f32_e32 v16, v16
	s_addc_u32 s1, s15, 0
	v_exp_f32_e32 v17, v17
	global_load_dwordx4 v[80:83], v154, s[100:101] offset:2048
	v_exp_f32_e32 v18, v18
	global_load_dwordx4 v[96:99], v158, s[0:1]
	v_exp_f32_e32 v19, v19
	global_load_dwordx4 v[84:87], v155, s[100:101] offset:2048
	v_exp_f32_e32 v20, v20
	global_load_dwordx4 v[100:103], v159, s[0:1]
	v_exp_f32_e32 v21, v21
	global_load_dwordx4 v[88:91], v156, s[100:101] offset:2048
	v_exp_f32_e32 v22, v22
	global_load_dwordx4 v[104:107], v160, s[0:1]
	v_exp_f32_e32 v23, v23
	global_load_dwordx4 v[92:95], v157, s[100:101] offset:2048
	v_exp_f32_e32 v24, v24
; __device__ __forceinline__ void attn_phase(const Params& P, char* smem_raw) {
;     ...
;         float rsum = 0.f;
; #pragma unroll
;         for (int t8 = 0; t8 < 8; ++t8) {
;           const float p = __builtin_amdgcn_exp2f(sacc[t8][reg] - mnew);
;           rsum += p;
;           sm_p[(wid * 16 + (lane_c >> 4) * 4 + reg) * 136 + t8 * 16 + (lane_c & 15)] = f2bf(p);
;         }
;         rsum = row16_sum(rsum);
;         lrow[reg] = lrow[reg] * alpha + rsum;
; #pragma unroll
;         for (int td = 0; td < 4; ++td) o[td][reg] *= alpha;
;       }
;       asm volatile("s_waitcnt lgkmcnt(0)" ::: "memory");
; #pragma unroll
;       for (int s4 = 0; s4 < 4; ++s4) {
;         const bf16x8 pf = *reinterpret_cast<const bf16x8*>(&sm_p[(wid * 16 + (lane_c & 15)) * 136 + s4 * 32 + (lane_c >> 4) * 8]);
; #pragma unroll
;         for (int td = 0; td < 4; ++td) {
;           const bf16x8 vf = *reinterpret_cast<const bf16x8*>(&sm_vt[(td * 16 + (lane_c & 15)) * 136 + s4 * 32 + (lane_c >> 4) * 8]);
;           o[td] = __builtin_amdgcn_mfma_f32_16x16x32_bf16(pf, vf, o[td], 0, 0, 0);
;         }
;       }
	global_load_dwordx4 v[108:111], v161, s[0:1]
	v_exp_f32_e32 v25, v25
	v_exp_f32_e32 v26, v26
	v_exp_f32_e32 v27, v27
	v_exp_f32_e32 v28, v28
	v_exp_f32_e32 v29, v29
	v_exp_f32_e32 v30, v30
	v_exp_f32_e32 v31, v31
	s_and_b32 s0, s3, 0xff
	s_add_u32 s0, s0, 1
	s_min_u32 s0, s0, 15
	s_lshr_b32 s1, s0, 2
	s_and_b32 s0, s0, 3
	s_lshl_b32 s0, s0, 5
	s_lshr_b32 vcc_lo, s3, 12
	s_add_u32 s0, s0, vcc_lo
	s_sub_i32 vcc_lo, s0, 4
	s_max_i32 vcc_lo, vcc_lo, 0
	s_min_i32 vcc_lo, vcc_lo, 0x78
	s_lshl_b32 vcc_hi, s1, 13
	s_sub_i32 vcc_lo, vcc_lo, s0
	s_add_i32 vcc_lo, vcc_lo, 4
	s_lshl_b32 vcc_lo, vcc_lo, 7
	s_bfe_u32 m0, s3, 0x10008
	s_mul_i32 m0, m0, 0x12000
	s_add_i32 vcc_lo, vcc_lo, m0
	s_add_i32 vcc_lo, vcc_lo, 0x10010
	v_add_u32_e32 v184, vcc_lo, v168
	v_add_u32_e32 v185, vcc_lo, v169
	v_add_u32_e32 v186, vcc_lo, v170
	v_add_u32_e32 v187, vcc_lo, v171
	v_add_u32_e32 v188, vcc_lo, v172
	v_add_u32_e32 v189, vcc_lo, v173
	v_add_u32_e32 v190, vcc_lo, v174
	v_add_u32_e32 v191, vcc_lo, v175
	ds_read_b128 v[112:115], v225 offset:0
	ds_read_b128 v[116:119], v225 offset:4096
	ds_read_b128 v[120:123], v225 offset:8192
	ds_read_b128 v[124:127], v225 offset:12288
	ds_read_b128 v[128:131], v226 offset:0
	ds_read_b128 v[132:135], v226 offset:4096
	ds_read_b128 v[136:139], v226 offset:8192
	ds_read_b128 v[140:143], v226 offset:12288
	v_mov_b32_e32 v221, v220
	v_pk_add_f32 v[222:223], v[0:1], v[2:3]
	v_pk_add_f32 v[222:223], v[222:223], v[4:5]
	v_pk_add_f32 v[222:223], v[222:223], v[6:7]
	v_pk_add_f32 v[222:223], v[222:223], v[8:9]
	v_pk_add_f32 v[222:223], v[222:223], v[10:11]
	v_pk_add_f32 v[222:223], v[222:223], v[12:13]
	v_pk_add_f32 v[222:223], v[222:223], v[14:15]
	v_pk_add_f32 v[222:223], v[222:223], v[16:17]
	v_pk_add_f32 v[222:223], v[222:223], v[18:19]
	v_pk_add_f32 v[222:223], v[222:223], v[20:21]
	v_pk_add_f32 v[222:223], v[222:223], v[22:23]
	v_pk_add_f32 v[222:223], v[222:223], v[24:25]
	v_pk_add_f32 v[222:223], v[222:223], v[26:27]
	v_pk_add_f32 v[222:223], v[222:223], v[28:29]
	v_pk_add_f32 v[222:223], v[222:223], v[30:31]
	v_pk_mul_f32 v[32:33], v[32:33], v[220:221]
	v_pk_mul_f32 v[34:35], v[34:35], v[220:221]
	v_pk_mul_f32 v[36:37], v[36:37], v[220:221]
	v_pk_mul_f32 v[38:39], v[38:39], v[220:221]
	v_pk_mul_f32 v[40:41], v[40:41], v[220:221]
	v_pk_mul_f32 v[42:43], v[42:43], v[220:221]
	v_pk_mul_f32 v[44:45], v[44:45], v[220:221]
	v_pk_mul_f32 v[46:47], v[46:47], v[220:221]
	v_add_f32_e32 v203, v222, v223
	v_fma_f32 v201, v201, v220, v203
	v_cvt_pk_bf16_f32 v48, v0, v1
	v_cvt_pk_bf16_f32 v49, v2, v3
	v_cvt_pk_bf16_f32 v50, v4, v5
	v_cvt_pk_bf16_f32 v51, v6, v7
	v_cvt_pk_bf16_f32 v52, v8, v9
	v_cvt_pk_bf16_f32 v53, v10, v11
	v_cvt_pk_bf16_f32 v54, v12, v13
	v_cvt_pk_bf16_f32 v55, v14, v15
	v_cvt_pk_bf16_f32 v56, v16, v17
	v_cvt_pk_bf16_f32 v57, v18, v19
	v_cvt_pk_bf16_f32 v58, v20, v21
	v_cvt_pk_bf16_f32 v59, v22, v23
	v_cvt_pk_bf16_f32 v60, v24, v25
	v_cvt_pk_bf16_f32 v61, v26, v27
	v_cvt_pk_bf16_f32 v62, v28, v29
	v_cvt_pk_bf16_f32 v63, v30, v31
	s_waitcnt lgkmcnt(7)
	v_mfma_f32_16x16x32_bf16 v[32:35], v[112:115], v[48:51], v[32:35]
	ds_read_b128 v[112:115], v227 offset:0
	s_waitcnt lgkmcnt(7)
	v_mfma_f32_16x16x32_bf16 v[36:39], v[116:119], v[48:51], v[36:39]
	ds_read_b128 v[116:119], v227 offset:4096
	s_waitcnt lgkmcnt(7)
	v_mfma_f32_16x16x32_bf16 v[40:43], v[120:123], v[48:51], v[40:43]
	ds_read_b128 v[120:123], v227 offset:8192
	s_waitcnt lgkmcnt(7)
	v_mfma_f32_16x16x32_bf16 v[44:47], v[124:127], v[48:51], v[44:47]
	ds_read_b128 v[124:127], v227 offset:12288
	s_waitcnt lgkmcnt(7)
	v_mfma_f32_16x16x32_bf16 v[32:35], v[128:131], v[52:55], v[32:35]
	ds_read_b128 v[128:131], v228 offset:0
	s_waitcnt lgkmcnt(7)
	v_mfma_f32_16x16x32_bf16 v[36:39], v[132:135], v[52:55], v[36:39]
	ds_read_b128 v[132:135], v228 offset:4096
	s_waitcnt lgkmcnt(7)
	v_mfma_f32_16x16x32_bf16 v[40:43], v[136:139], v[52:55], v[40:43]
	ds_read_b128 v[136:139], v228 offset:8192
	s_waitcnt lgkmcnt(7)
	v_mfma_f32_16x16x32_bf16 v[44:47], v[140:143], v[52:55], v[44:47]
	ds_read_b128 v[140:143], v228 offset:12288
	s_waitcnt lgkmcnt(7)
	v_mfma_f32_16x16x32_bf16 v[32:35], v[112:115], v[56:59], v[32:35]
	s_waitcnt lgkmcnt(6)
	v_mfma_f32_16x16x32_bf16 v[36:39], v[116:119], v[56:59], v[36:39]
	s_waitcnt lgkmcnt(5)
	v_mfma_f32_16x16x32_bf16 v[40:43], v[120:123], v[56:59], v[40:43]
	s_waitcnt lgkmcnt(4)
	v_mfma_f32_16x16x32_bf16 v[44:47], v[124:127], v[56:59], v[44:47]
	s_waitcnt lgkmcnt(3)
	v_mfma_f32_16x16x32_bf16 v[32:35], v[128:131], v[60:63], v[32:35]
	s_waitcnt lgkmcnt(2)
	v_mfma_f32_16x16x32_bf16 v[36:39], v[132:135], v[60:63], v[36:39]
	s_waitcnt lgkmcnt(1)
	v_mfma_f32_16x16x32_bf16 v[40:43], v[136:139], v[60:63], v[40:43]
	s_waitcnt lgkmcnt(0)
	v_mfma_f32_16x16x32_bf16 v[44:47], v[140:143], v[60:63], v[44:47]
	s_barrier
; __device__ __forceinline__ void attn_phase(const Params& P, char* smem_raw) {
;     ...
;       __syncthreads();
;       f32x4 sacc[8];
; #pragma unroll
;       for (int t8 = 0; t8 < 8; ++t8) sacc[t8] = f32x4{0.f, 0.f, 0.f, 0.f};
; #pragma unroll
;       for (int s = 0; s < 2; ++s)
; #pragma unroll
;         for (int t8 = 0; t8 < 8; ++t8) {
;           const bf16x8 kf = *reinterpret_cast<const bf16x8*>(&sm_k[(t8 * 16 + (lane_c & 15)) * LDSS + s * 32 + (lane_c >> 4) * 8]);
;           sacc[t8] = __builtin_amdgcn_mfma_f32_16x16x32_bf16(qf[s], kf, sacc[t8], 0, 0, 0);
;         }
;       if (ck < 5) {
;         ATT_ISSUE(t, ck + 1)
;       } else if (t + VGRID < 8192) {
;         ATT_ISSUE(t + VGRID, 0)
;         ATT_QLOAD(t + VGRID)
;       }
;       if (ck < 4) {
;         const float* rb0 = sm_rpb + (rs + ck * 2 - r + 7) * 31;
; #pragma unroll
;         for (int t8 = 0; t8 < 8; ++t8)
; #pragma unroll
;           for (int reg = 0; reg < 4; ++reg)
;             sacc[t8][reg] += rb0[(t8 >> 2) * 31 + dco[reg][t8 & 3]];
;       }
; #pragma unroll
;       for (int reg = 0; reg < 4; ++reg) {
;         float mx = sacc[0][reg];
; #pragma unroll
;         for (int t8 = 1; t8 < 8; ++t8) mx = fmaxf(mx, sacc[t8][reg]);
;         mx = row16_max(mx);
	ds_read_b128 v[112:115], v149 offset:32768
	ds_read_b128 v[116:119], v224 offset:32768
	ds_read_b128 v[120:123], v149 offset:40960
	ds_read_b128 v[124:127], v224 offset:40960
	ds_read_b128 v[128:131], v149 offset:34816
	ds_read_b128 v[132:135], v224 offset:34816
	ds_read_b128 v[136:139], v149 offset:43008
	ds_read_b128 v[140:143], v224 offset:43008
	s_waitcnt lgkmcnt(7)
	v_mfma_f32_16x16x32_bf16 v[0:3], v[112:115], v[64:67], 0
	ds_read_b128 v[112:115], v149 offset:36864
	s_waitcnt lgkmcnt(7)
	v_mfma_f32_16x16x32_bf16 v[0:3], v[116:119], v[68:71], v[0:3]
	ds_read_b128 v[116:119], v224 offset:36864
	s_waitcnt lgkmcnt(7)
	v_mfma_f32_16x16x32_bf16 v[4:7], v[120:123], v[64:67], 0
	ds_read_b128 v[120:123], v149 offset:45056
	s_waitcnt lgkmcnt(7)
	v_mfma_f32_16x16x32_bf16 v[4:7], v[124:127], v[68:71], v[4:7]
	ds_read_b128 v[124:127], v224 offset:45056
	s_waitcnt lgkmcnt(7)
	v_mfma_f32_16x16x32_bf16 v[8:11], v[128:131], v[64:67], 0
	ds_read_b128 v[128:131], v149 offset:38912
	s_waitcnt lgkmcnt(7)
	v_mfma_f32_16x16x32_bf16 v[8:11], v[132:135], v[68:71], v[8:11]
	ds_read_b128 v[132:135], v224 offset:38912
	s_waitcnt lgkmcnt(7)
	v_mfma_f32_16x16x32_bf16 v[12:15], v[136:139], v[64:67], 0
	ds_read_b128 v[136:139], v149 offset:47104
	s_waitcnt lgkmcnt(7)
	v_mfma_f32_16x16x32_bf16 v[12:15], v[140:143], v[68:71], v[12:15]
	ds_read_b128 v[140:143], v224 offset:47104
	s_waitcnt lgkmcnt(7)
	v_mfma_f32_16x16x32_bf16 v[16:19], v[112:115], v[64:67], 0
	s_waitcnt lgkmcnt(6)
	v_mfma_f32_16x16x32_bf16 v[16:19], v[116:119], v[68:71], v[16:19]
	s_waitcnt lgkmcnt(5)
	v_mfma_f32_16x16x32_bf16 v[20:23], v[120:123], v[64:67], 0
	s_waitcnt lgkmcnt(4)
	v_mfma_f32_16x16x32_bf16 v[20:23], v[124:127], v[68:71], v[20:23]
	s_waitcnt lgkmcnt(3)
	v_mfma_f32_16x16x32_bf16 v[24:27], v[128:131], v[64:67], 0
	s_waitcnt lgkmcnt(2)
	v_mfma_f32_16x16x32_bf16 v[24:27], v[132:135], v[68:71], v[24:27]
	s_waitcnt lgkmcnt(1)
	v_mfma_f32_16x16x32_bf16 v[28:31], v[136:139], v[64:67], 0
	s_waitcnt lgkmcnt(0)
	v_mfma_f32_16x16x32_bf16 v[28:31], v[140:143], v[68:71], v[28:31]
	s_nop 7
	v_max3_f32 v203, v0, v1, v2
	v_max3_f32 v203, v203, v3, v4
	v_max3_f32 v203, v203, v5, v6
	v_max3_f32 v203, v203, v7, v8
	v_max3_f32 v203, v203, v9, v10
	v_max3_f32 v203, v203, v11, v12
	v_max3_f32 v203, v203, v13, v14
	v_max3_f32 v203, v203, v15, v16
	v_max3_f32 v203, v203, v17, v18
	v_max3_f32 v203, v203, v19, v20
	v_max3_f32 v203, v203, v21, v22
	v_max3_f32 v203, v203, v23, v24
	v_max3_f32 v203, v203, v25, v26
	v_max3_f32 v203, v203, v27, v28
	v_max3_f32 v203, v203, v29, v30
	v_max_f32_e32 v203, v203, v31
	v_mov_b32_e32 v205, v203
	s_nop 1
	v_permlane16_swap_b32_e32 v203, v205
	v_max_f32_e32 v203, v203, v205
	v_mov_b32_e32 v205, v203
	s_nop 1
	v_permlane32_swap_b32_e32 v203, v205
	v_max_f32_e32 v203, v203, v205
	v_max_f32_e32 v218, v200, v203
	v_sub_f32_e32 v220, v200, v218
	v_mov_b32_e32 v219, v218
	v_exp_f32_e32 v220, v220
	v_mov_b32_e32 v200, v218
	v_pk_add_f32 v[0:1], v[0:1], v[218:219] neg_lo:[0,1] neg_hi:[0,1]
	v_pk_add_f32 v[2:3], v[2:3], v[218:219] neg_lo:[0,1] neg_hi:[0,1]
	v_pk_add_f32 v[4:5], v[4:5], v[218:219] neg_lo:[0,1] neg_hi:[0,1]
	v_pk_add_f32 v[6:7], v[6:7], v[218:219] neg_lo:[0,1] neg_hi:[0,1]
	v_pk_add_f32 v[8:9], v[8:9], v[218:219] neg_lo:[0,1] neg_hi:[0,1]
	v_pk_add_f32 v[10:11], v[10:11], v[218:219] neg_lo:[0,1] neg_hi:[0,1]
	v_pk_add_f32 v[12:13], v[12:13], v[218:219] neg_lo:[0,1] neg_hi:[0,1]
	v_pk_add_f32 v[14:15], v[14:15], v[218:219] neg_lo:[0,1] neg_hi:[0,1]
	v_pk_add_f32 v[16:17], v[16:17], v[218:219] neg_lo:[0,1] neg_hi:[0,1]
	v_pk_add_f32 v[18:19], v[18:19], v[218:219] neg_lo:[0,1] neg_hi:[0,1]
	v_pk_add_f32 v[20:21], v[20:21], v[218:219] neg_lo:[0,1] neg_hi:[0,1]
	v_pk_add_f32 v[22:23], v[22:23], v[218:219] neg_lo:[0,1] neg_hi:[0,1]
	v_pk_add_f32 v[24:25], v[24:25], v[218:219] neg_lo:[0,1] neg_hi:[0,1]
	v_pk_add_f32 v[26:27], v[26:27], v[218:219] neg_lo:[0,1] neg_hi:[0,1]
	v_pk_add_f32 v[28:29], v[28:29], v[218:219] neg_lo:[0,1] neg_hi:[0,1]
	v_pk_add_f32 v[30:31], v[30:31], v[218:219] neg_lo:[0,1] neg_hi:[0,1]
	v_exp_f32_e32 v0, v0
	s_waitcnt vmcnt(0)
	v_exp_f32_e32 v1, v1
	ds_write_b128 v150, v[80:83] offset:0
	v_exp_f32_e32 v2, v2
	ds_write_b128 v150, v[84:87] offset:4096
	v_exp_f32_e32 v3, v3
	ds_write_b128 v150, v[88:91] offset:8192
	v_exp_f32_e32 v4, v4
	ds_write_b128 v150, v[92:95] offset:12288
	v_exp_f32_e32 v5, v5
	ds_write_b64 v151, v[96:97] offset:0
	v_exp_f32_e32 v6, v6
	ds_write_b64 v229, v[98:99] offset:0
	v_exp_f32_e32 v7, v7
	ds_write_b64 v151, v[100:101] offset:4096
	v_exp_f32_e32 v8, v8
	ds_write_b64 v229, v[102:103] offset:4096
	v_exp_f32_e32 v9, v9
	ds_write_b64 v151, v[104:105] offset:8192
	v_exp_f32_e32 v10, v10
	ds_write_b64 v229, v[106:107] offset:8192
	v_exp_f32_e32 v11, v11
	ds_write_b64 v151, v[108:109] offset:12288
	v_exp_f32_e32 v12, v12
	ds_write_b64 v229, v[110:111] offset:12288
	v_exp_f32_e32 v13, v13
	s_add_u32 s100, s12, 0xc0000
	v_exp_f32_e32 v14, v14
	s_addc_u32 s101, s13, 0
	v_exp_f32_e32 v15, v15
	s_add_u32 s0, s14, 0x100
	v_exp_f32_e32 v16, v16
	s_addc_u32 s1, s15, 0
	v_exp_f32_e32 v17, v17
	global_load_dwordx4 v[80:83], v154, s[100:101] offset:2048
	v_exp_f32_e32 v18, v18
	global_load_dwordx4 v[96:99], v158, s[0:1]
	v_exp_f32_e32 v19, v19
	global_load_dwordx4 v[84:87], v155, s[100:101] offset:2048
	v_exp_f32_e32 v20, v20
	global_load_dwordx4 v[100:103], v159, s[0:1]
	v_exp_f32_e32 v21, v21
	global_load_dwordx4 v[88:91], v156, s[100:101] offset:2048
	v_exp_f32_e32 v22, v22
	global_load_dwordx4 v[104:107], v160, s[0:1]
	v_exp_f32_e32 v23, v23
	global_load_dwordx4 v[92:95], v157, s[100:101] offset:2048
	v_exp_f32_e32 v24, v24
; __device__ __forceinline__ void attn_phase(const Params& P, char* smem_raw) {
;     ...
;         float rsum = 0.f;
; #pragma unroll
;         for (int t8 = 0; t8 < 8; ++t8) {
;           const float p = __builtin_amdgcn_exp2f(sacc[t8][reg] - mnew);
;           rsum += p;
;           sm_p[(wid * 16 + (lane_c >> 4) * 4 + reg) * 136 + t8 * 16 + (lane_c & 15)] = f2bf(p);
;         }
;         rsum = row16_sum(rsum);
;         lrow[reg] = lrow[reg] * alpha + rsum;
; #pragma unroll
;         for (int td = 0; td < 4; ++td) o[td][reg] *= alpha;
;       }
;       asm volatile("s_waitcnt lgkmcnt(0)" ::: "memory");
; #pragma unroll
;       for (int s4 = 0; s4 < 4; ++s4) {
;         const bf16x8 pf = *reinterpret_cast<const bf16x8*>(&sm_p[(wid * 16 + (lane_c & 15)) * 136 + s4 * 32 + (lane_c >> 4) * 8]);
; #pragma unroll
;         for (int td = 0; td < 4; ++td) {
;           const bf16x8 vf = *reinterpret_cast<const bf16x8*>(&sm_vt[(td * 16 + (lane_c & 15)) * 136 + s4 * 32 + (lane_c >> 4) * 8]);
;           o[td] = __builtin_amdgcn_mfma_f32_16x16x32_bf16(pf, vf, o[td], 0, 0, 0);
;         }
;       }
;     }
;     u16* Ob = P.cat + ((long)b * 8192 + r * 64) * 1024 + h * 64;
; #pragma unroll
;     for (int td = 0; td < 4; ++td)
; #pragma unroll
;       for (int reg = 0; reg < 4; ++reg) {
;         const int rowl = wid * 16 + (lane >> 4) * 4 + reg;
;         Ob[(unsigned)(rowl * 1024 + td * 16 + (lane & 15))] = f2bf(o[td][reg] * __builtin_amdgcn_rcpf(lrow[reg]));
;       }
	global_load_dwordx4 v[108:111], v161, s[0:1]
	v_exp_f32_e32 v25, v25
	v_exp_f32_e32 v26, v26
	v_exp_f32_e32 v27, v27
	v_exp_f32_e32 v28, v28
	v_exp_f32_e32 v29, v29
	v_exp_f32_e32 v30, v30
	v_exp_f32_e32 v31, v31
	ds_read_b128 v[112:115], v225 offset:32768
	ds_read_b128 v[116:119], v225 offset:36864
	ds_read_b128 v[120:123], v225 offset:40960
	ds_read_b128 v[124:127], v225 offset:45056
	ds_read_b128 v[128:131], v226 offset:32768
	ds_read_b128 v[132:135], v226 offset:36864
	ds_read_b128 v[136:139], v226 offset:40960
	ds_read_b128 v[140:143], v226 offset:45056
	v_mov_b32_e32 v221, v220
	v_pk_add_f32 v[222:223], v[0:1], v[2:3]
	v_pk_add_f32 v[222:223], v[222:223], v[4:5]
	v_pk_add_f32 v[222:223], v[222:223], v[6:7]
	v_pk_add_f32 v[222:223], v[222:223], v[8:9]
	v_pk_add_f32 v[222:223], v[222:223], v[10:11]
	v_pk_add_f32 v[222:223], v[222:223], v[12:13]
	v_pk_add_f32 v[222:223], v[222:223], v[14:15]
	v_pk_add_f32 v[222:223], v[222:223], v[16:17]
	v_pk_add_f32 v[222:223], v[222:223], v[18:19]
	v_pk_add_f32 v[222:223], v[222:223], v[20:21]
	v_pk_add_f32 v[222:223], v[222:223], v[22:23]
	v_pk_add_f32 v[222:223], v[222:223], v[24:25]
	v_pk_add_f32 v[222:223], v[222:223], v[26:27]
	v_pk_add_f32 v[222:223], v[222:223], v[28:29]
	v_pk_add_f32 v[222:223], v[222:223], v[30:31]
	v_pk_mul_f32 v[32:33], v[32:33], v[220:221]
	v_pk_mul_f32 v[34:35], v[34:35], v[220:221]
	v_pk_mul_f32 v[36:37], v[36:37], v[220:221]
	v_pk_mul_f32 v[38:39], v[38:39], v[220:221]
	v_pk_mul_f32 v[40:41], v[40:41], v[220:221]
	v_pk_mul_f32 v[42:43], v[42:43], v[220:221]
	v_pk_mul_f32 v[44:45], v[44:45], v[220:221]
	v_pk_mul_f32 v[46:47], v[46:47], v[220:221]
	v_add_f32_e32 v203, v222, v223
	v_fma_f32 v201, v201, v220, v203
	v_cvt_pk_bf16_f32 v48, v0, v1
	v_cvt_pk_bf16_f32 v49, v2, v3
	v_cvt_pk_bf16_f32 v50, v4, v5
	v_cvt_pk_bf16_f32 v51, v6, v7
	v_cvt_pk_bf16_f32 v52, v8, v9
	v_cvt_pk_bf16_f32 v53, v10, v11
	v_cvt_pk_bf16_f32 v54, v12, v13
	v_cvt_pk_bf16_f32 v55, v14, v15
	v_cvt_pk_bf16_f32 v56, v16, v17
	v_cvt_pk_bf16_f32 v57, v18, v19
	v_cvt_pk_bf16_f32 v58, v20, v21
	v_cvt_pk_bf16_f32 v59, v22, v23
	v_cvt_pk_bf16_f32 v60, v24, v25
	v_cvt_pk_bf16_f32 v61, v26, v27
	v_cvt_pk_bf16_f32 v62, v28, v29
	v_cvt_pk_bf16_f32 v63, v30, v31
	s_waitcnt lgkmcnt(7)
	v_mfma_f32_16x16x32_bf16 v[32:35], v[112:115], v[48:51], v[32:35]
	ds_read_b128 v[112:115], v227 offset:32768
	s_waitcnt lgkmcnt(7)
	v_mfma_f32_16x16x32_bf16 v[36:39], v[116:119], v[48:51], v[36:39]
	ds_read_b128 v[116:119], v227 offset:36864
	s_waitcnt lgkmcnt(7)
	v_mfma_f32_16x16x32_bf16 v[40:43], v[120:123], v[48:51], v[40:43]
	ds_read_b128 v[120:123], v227 offset:40960
	s_waitcnt lgkmcnt(7)
	v_mfma_f32_16x16x32_bf16 v[44:47], v[124:127], v[48:51], v[44:47]
	ds_read_b128 v[124:127], v227 offset:45056
	s_waitcnt lgkmcnt(7)
	v_mfma_f32_16x16x32_bf16 v[32:35], v[128:131], v[52:55], v[32:35]
	ds_read_b128 v[128:131], v228 offset:32768
	s_waitcnt lgkmcnt(7)
	v_mfma_f32_16x16x32_bf16 v[36:39], v[132:135], v[52:55], v[36:39]
	ds_read_b128 v[132:135], v228 offset:36864
	s_waitcnt lgkmcnt(7)
	v_mfma_f32_16x16x32_bf16 v[40:43], v[136:139], v[52:55], v[40:43]
	ds_read_b128 v[136:139], v228 offset:40960
	s_waitcnt lgkmcnt(7)
	v_mfma_f32_16x16x32_bf16 v[44:47], v[140:143], v[52:55], v[44:47]
	ds_read_b128 v[140:143], v228 offset:45056
	s_waitcnt lgkmcnt(7)
	v_mfma_f32_16x16x32_bf16 v[32:35], v[112:115], v[56:59], v[32:35]
	s_waitcnt lgkmcnt(6)
	v_mfma_f32_16x16x32_bf16 v[36:39], v[116:119], v[56:59], v[36:39]
	s_waitcnt lgkmcnt(5)
	v_mfma_f32_16x16x32_bf16 v[40:43], v[120:123], v[56:59], v[40:43]
	s_waitcnt lgkmcnt(4)
	v_mfma_f32_16x16x32_bf16 v[44:47], v[124:127], v[56:59], v[44:47]
	s_waitcnt lgkmcnt(3)
	v_mfma_f32_16x16x32_bf16 v[32:35], v[128:131], v[60:63], v[32:35]
	s_waitcnt lgkmcnt(2)
	v_mfma_f32_16x16x32_bf16 v[36:39], v[132:135], v[60:63], v[36:39]
	s_waitcnt lgkmcnt(1)
	v_mfma_f32_16x16x32_bf16 v[40:43], v[136:139], v[60:63], v[40:43]
	s_waitcnt lgkmcnt(0)
	v_mfma_f32_16x16x32_bf16 v[44:47], v[140:143], v[60:63], v[44:47]
	ds_read_b32 v0, v184 offset:384
	ds_read_b32 v1, v185 offset:384
	ds_read_b32 v2, v186 offset:384
	ds_read_b32 v3, v187 offset:384
	ds_read_b32 v4, v184 offset:512
	ds_read_b32 v5, v185 offset:512
	ds_read_b32 v6, v186 offset:512
	ds_read_b32 v7, v187 offset:512
	ds_read_b32 v8, v188 offset:384
	ds_read_b32 v9, v189 offset:384
	ds_read_b32 v10, v190 offset:384
	ds_read_b32 v11, v191 offset:384
	ds_read_b32 v12, v188 offset:512
	ds_read_b32 v13, v189 offset:512
	ds_read_b32 v14, v190 offset:512
	ds_read_b32 v15, v191 offset:512
	v_mov_b32_e32 v205, v201
	s_nop 1
	v_permlane16_swap_b32_e32 v201, v205
	v_add_f32_e32 v201, v201, v205
	v_mov_b32_e32 v205, v201
	s_nop 1
	v_permlane32_swap_b32_e32 v201, v205
	v_add_f32_e32 v201, v201, v205
	v_rcp_f32_e32 v203, v201
	s_nop 7
	v_mul_f32_e32 v32, v32, v203
	v_mul_f32_e32 v33, v33, v203
	v_mul_f32_e32 v34, v34, v203
	v_mul_f32_e32 v35, v35, v203
	v_mul_f32_e32 v36, v36, v203
	v_mul_f32_e32 v37, v37, v203
	v_mul_f32_e32 v38, v38, v203
	v_mul_f32_e32 v39, v39, v203
	v_mul_f32_e32 v40, v40, v203
	v_mul_f32_e32 v41, v41, v203
	v_mul_f32_e32 v42, v42, v203
	v_mul_f32_e32 v43, v43, v203
	v_mul_f32_e32 v44, v44, v203
	v_mul_f32_e32 v45, v45, v203
	v_mul_f32_e32 v46, v46, v203
	v_mul_f32_e32 v47, v47, v203
	v_cvt_pk_bf16_f32 v210, v32, v33
	v_cvt_pk_bf16_f32 v211, v34, v35
	v_cvt_pk_bf16_f32 v212, v36, v37
	v_cvt_pk_bf16_f32 v213, v38, v39
	v_cvt_pk_bf16_f32 v214, v40, v41
	v_cvt_pk_bf16_f32 v215, v42, v43
	v_cvt_pk_bf16_f32 v216, v44, v45
	v_cvt_pk_bf16_f32 v217, v46, v47
	global_store_dwordx2 v167, v[210:211], s[98:99] offset:0
	global_store_dwordx2 v167, v[212:213], s[98:99] offset:32
	global_store_dwordx2 v167, v[214:215], s[98:99] offset:64
	global_store_dwordx2 v167, v[216:217], s[98:99] offset:96
	v_mov_b32_e32 v200, 0xf149f2ca
	v_mov_b32_e32 v201, 0
	v_mov_b32_e32 v32, 0
	v_mov_b32_e32 v33, 0
	v_mov_b32_e32 v34, 0
	v_mov_b32_e32 v35, 0
	v_mov_b32_e32 v36, 0
	v_mov_b32_e32 v37, 0
	v_mov_b32_e32 v38, 0
	v_mov_b32_e32 v39, 0
	v_mov_b32_e32 v40, 0
	v_mov_b32_e32 v41, 0
	v_mov_b32_e32 v42, 0
	v_mov_b32_e32 v43, 0
	v_mov_b32_e32 v44, 0
	v_mov_b32_e32 v45, 0
	v_mov_b32_e32 v46, 0
	v_mov_b32_e32 v47, 0
	v_mov_b32_e32 v64, v72
	v_mov_b32_e32 v65, v73
	v_mov_b32_e32 v66, v74
	v_mov_b32_e32 v67, v75
	v_mov_b32_e32 v68, v76
	v_mov_b32_e32 v69, v77
	v_mov_b32_e32 v70, v78
	v_mov_b32_e32 v71, v79
	s_add_u32 s3, s3, 1
	s_and_b32 s0, s3, 0xff
	s_cmp_lt_u32 s0, 16
	s_cbranch_scc1 .Lmy_att_tile
	s_waitcnt vmcnt(0) lgkmcnt(0)
	s_branch .LBB0_1501
